# mod-item release: drop the cache invalidate from the release fence before the arrival atomic (write-back + wait kept; the acquire side in wait_mod keeps its invalidate)
# baseline (speedup 1.0000x reference)
; DI void phase0a(const Params& p, char* smem) {
;     ...
;   for (int it = blockIdx.x; it < nMod; it += gridDim.x) {
;     mod_item(p, it, smem);
;     __syncthreads();
;     if (t == 0) { __threadfence(); atomicAdd(p.modctr, 1u); }
;   }
.LBB0_14:
	s_or_b64 exec, exec, s[4:5]
	s_barrier
	s_and_saveexec_b64 s[4:5], s[6:7]
	s_cbranch_execz .LBB0_2
	s_mov_b64 s[10:11], exec
	v_mbcnt_lo_u32_b32 v1, s10, 0
	v_mbcnt_hi_u32_b32 v1, s11, v1
	v_cmp_eq_u32_e32 vcc, 0, v1
	s_and_b64 s[22:23], exec, vcc
	buffer_wbl2 sc1
	s_waitcnt vmcnt(0)
	s_mov_b64 exec, s[22:23]
	s_cbranch_execz .LBB0_2
	s_bcnt1_i32_b64 s10, s[10:11]
	v_mov_b32_e32 v1, s10
	global_atomic_add v7, v1, s[20:21]
	s_branch .LBB0_2
